# attn_prompt: K fragments of the next key pair prefetched into spare VGPRs one iteration ahead, score MFMAs of the two tiles interleaved
# baseline (speedup 1.0000x reference)
; #define LAS __attribute__((address_space(3)))
; __device__ __forceinline__ void attn_prompt(const Params& p, int j, LAS unsigned char* lds, const int wave, const int lane) {
;     ...
;         for (int kp = kp0; kp < 5; ++kp) {
;             const int kbase = q0 - 144 + 32 * kp, lrow = 16 * wave + 32 * kp;
;             f32x4 st[2];
; #pragma unroll
;             for (int tl = 0; tl < 2; ++tl) {
;                 const LAS unsigned char* kr = Kl + (lrow + tl * 16 + fr) * 144 + g4 * 16;
;                 const bf16x8 kf0 = *(const LAS bf16x8*)kr, kf1 = *(const LAS bf16x8*)(kr + 64);
;                 f32x4 sv = (f32x4){0.f, 0.f, 0.f, 0.f};
;                 sv = __builtin_amdgcn_mfma_f32_16x16x32_bf16(kf0, qf0, sv, 0, 0, 0);
;                 sv = __builtin_amdgcn_mfma_f32_16x16x32_bf16(kf1, qf1, sv, 0, 0, 0);
;                 st[tl] = sv;
;             }
;             float mx = -1e30f; bool val[2][4];
; #pragma unroll
;             for (int tl = 0; tl < 2; ++tl)
; #pragma unroll
;                 for (int e = 0; e < 4; ++e) { const int uk = kbase + tl * 16 + g4 * 4 + e, dist = uq - uk; val[tl][e] = (uk >= 0) && (dist >= 0) && (dist <= 128);
;                     st[tl][e] = val[tl][e] ? st[tl][e] * 0.125f : -1e30f; mx = fmaxf(mx, st[tl][e]); }
;             mx = xmax4(mx);
;             const float mnew = fmaxf(mrun, mx), sc = __expf(mrun - mnew);
;             mrun = mnew; lrun *= sc;
; #pragma unroll
;             for (int dt = 0; dt < 4; ++dt) acc[dt] = acc[dt] * sc;
;             float pv[2][4];
; #pragma unroll
;             for (int tl = 0; tl < 2; ++tl)
; #pragma unroll
;                 for (int e = 0; e < 4; ++e) { pv[tl][e] = val[tl][e] ? __expf(st[tl][e] - mnew) : 0.f; lrun += pv[tl][e]; }
;             bf16x8 pf;
;             { u32x4 w; w.x = pk2(pv[0][0], pv[0][1]); w.y = pk2(pv[0][2], pv[0][3]); w.z = pk2(pv[1][0], pv[1][1]); w.w = pk2(pv[1][2], pv[1][3]); pf = __builtin_bit_cast(bf16x8, w); }
; #pragma unroll
;             for (int dt = 0; dt < 4; ++dt) {
;                 LAS unsigned char* ta = Vl + (lrow + g4 * 4 + (fr >> 2)) * 136 + dt * 32 + 8 * (fr & 3);
;                 const s16x4_ lo = __builtin_amdgcn_ds_read_tr16_b64_v4i16((LAS s16x4_*)ta), hi = __builtin_amdgcn_ds_read_tr16_b64_v4i16((LAS s16x4_*)(ta + 2176));
;                 const bf16x8 vf = (bf16x8){lo[0], lo[1], lo[2], lo[3], hi[0], hi[1], hi[2], hi[3]};
.LBB0_311:
	s_ashr_i32 s12, s7, 10
	s_lshl_b32 s17, s12, 1
	s_lshr_b32 s24, 16, s17
	s_and_b32 s13, s7, 0x3ff
	s_add_i32 s24, s24, -1
	s_and_b32 s24, s24, s13
	s_lshl_b32 s26, s24, 7
	s_add_i32 s24, s26, s0
	s_sub_i32 s25, 0x90, s24
	s_lshr_b32 s25, s25, 5
	s_cmpk_lt_i32 s24, 0x71
	s_cselect_b32 s27, s25, 0
	s_cmp_gt_u32 s27, 4
	s_cbranch_scc1 .LBB0_314
	s_lshl_b32 s30, s27, 5
	s_add_i32 s26, s30, s26
	v_add_u32_e32 v56, s30, v79
	s_add_i32 s25, s27, -1
	v_add_u32_e32 v83, s26, v94
	v_mad_u64_u32 v[84:85], s[26:27], v56, s56, v[76:77]
	v_add_u32_e32 v56, s30, v96
	v_mad_u64_u32 v[86:87], s[26:27], v56, s34, v[78:79]
	v_mov_b32_e32 v72, 0
	v_subrev_u32_e32 v81, s30, v93
	v_add_u32_e32 v107, s30, v95
	v_mov_b32_e32 v85, 0xf149f2ca
	v_mov_b32_e32 v68, 0
	v_mov_b32_e32 v69, v72
	v_mov_b32_e32 v70, v72
	v_mov_b32_e32 v71, v72
	v_mov_b32_e32 v64, 0
	v_mov_b32_e32 v65, v72
	v_mov_b32_e32 v66, v72
	v_mov_b32_e32 v67, v72
	v_mov_b32_e32 v60, 0
	v_mov_b32_e32 v61, v72
	v_mov_b32_e32 v62, v72
	v_mov_b32_e32 v63, v72
	v_mov_b32_e32 v56, 0
	v_mov_b32_e32 v57, v72
	v_mov_b32_e32 v58, v72
	v_mov_b32_e32 v59, v72
	s_mov_b32 s27, 0xffff0000
	ds_read_b128 v[136:139], v84
	ds_read_b128 v[140:143], v84 offset:64
	ds_read_b128 v[144:147], v84 offset:2304
	ds_read_b128 v[148:151], v84 offset:2368
.LBB0_313:
	ds_read_b64_tr_b16 v[120:121], v86 offset:39424
	ds_read_b64_tr_b16 v[122:123], v86 offset:41600
	ds_read_b64_tr_b16 v[124:125], v86 offset:39456
	ds_read_b64_tr_b16 v[126:127], v86 offset:41632
	ds_read_b64_tr_b16 v[128:129], v86 offset:39488
	ds_read_b64_tr_b16 v[130:131], v86 offset:41664
	ds_read_b64_tr_b16 v[132:133], v86 offset:39520
	ds_read_b64_tr_b16 v[134:135], v86 offset:41696
	v_mov_b32_e32 v73, v85
	v_add_u32_e32 v85, 17, v81
	v_cmp_lt_i32_e64 s[52:53], -1, v83
	s_waitcnt lgkmcnt(8)
	v_mfma_f32_16x16x32_bf16 v[108:111], v[136:139], v[40:43], 0
	v_cmp_gt_u32_e64 s[50:51], s35, v85
	s_and_b64 s[50:51], s[52:53], s[50:51]
	s_movk_i32 s26, 0xff7e
	v_mfma_f32_16x16x32_bf16 v[112:115], v[144:147], v[40:43], 0
	v_mfma_f32_16x16x32_bf16 v[108:111], v[140:143], v[44:47], v[108:111]
	v_mfma_f32_16x16x32_bf16 v[112:115], v[148:151], v[44:47], v[112:115]
	ds_read_b128 v[136:139], v84 offset:4608
	ds_read_b128 v[140:143], v84 offset:4672
	ds_read_b128 v[144:147], v84 offset:6912
	ds_read_b128 v[148:151], v84 offset:6976
	v_add_u32_e32 v74, 19, v81
	v_cmp_gt_u32_e32 vcc, s35, v74
	s_nop 1
	v_mul_f32_e32 v85, 0x3e000000, v110
	v_mul_f32_e32 v74, 0x3e000000, v108
	v_cndmask_b32_e64 v108, v221, v85, s[50:51]
	v_add_u32_e32 v85, 16, v81
	v_cmp_lt_u32_e64 s[48:49], s26, v107
	v_cmp_gt_u32_e64 s[54:55], s35, v85
	s_and_b64 vcc, s[52:53], vcc
	s_and_b64 s[48:49], s[52:53], s[48:49]
	s_and_b64 s[52:53], s[52:53], s[54:55]
	v_mul_f32_e32 v85, 0x3e000000, v111
	v_cndmask_b32_e32 v75, v221, v74, vcc
	v_mul_f32_e32 v74, 0x3e000000, v109
	v_cndmask_b32_e64 v109, v221, v85, s[52:53]
	v_add_u32_e32 v85, 16, v83
	v_cmp_lt_i32_e64 s[58:59], -1, v85
	v_add_u32_e32 v85, 3, v81
	v_cmp_gt_u32_e64 s[54:55], s35, v85
	s_and_b64 s[54:55], s[58:59], s[54:55]
	v_mul_f32_e32 v85, 0x3e000000, v112
	v_cndmask_b32_e64 v110, v221, v85, s[54:55]
	v_add_u32_e32 v85, 2, v81
	v_cmp_gt_u32_e64 s[60:61], s35, v85
	s_and_b64 s[60:61], s[58:59], s[60:61]
	v_mul_f32_e32 v85, 0x3e000000, v113
	v_cndmask_b32_e64 v111, v221, v85, s[60:61]
	v_add_u32_e32 v85, 1, v81
	v_cndmask_b32_e64 v87, v221, v74, s[48:49]
	s_mov_b32 s26, 0xf149f2ca
	v_cmp_gt_u32_e64 s[62:63], s35, v85
	v_max3_f32 v74, v75, s26, v87
	s_and_b64 s[62:63], s[58:59], s[62:63]
	v_mul_f32_e32 v85, 0x3e000000, v114
	v_cmp_gt_u32_e64 s[64:65], s35, v81
	v_max3_f32 v74, v74, v108, v109
	v_cndmask_b32_e64 v112, v221, v85, s[62:63]
	s_and_b64 s[58:59], s[58:59], s[64:65]
	v_mul_f32_e32 v85, 0x3e000000, v115
	v_max3_f32 v74, v74, v110, v111
	v_cndmask_b32_e64 v113, v221, v85, s[58:59]
	v_max3_f32 v74, v74, v112, v113
	v_mov_b32_e32 v85, v74
	s_nop 1
	v_permlane16_swap_b32 v74, v85
	s_add_i32 s25, s25, 1
	v_max_f32_e32 v85, v85, v85
	v_max_f32_e32 v74, v74, v74
	v_max_f32_e32 v74, v74, v85
	v_mov_b32_e32 v85, v74
	s_nop 1
	v_permlane32_swap_b32 v74, v85
	v_subrev_u32_e32 v81, 32, v81
	v_max3_f32 v85, v73, v74, v85
	v_sub_f32_e32 v73, v73, v85
	v_mul_f32_e32 v73, 0x3fb8aa3b, v73
	v_exp_f32_e32 v74, v73
	v_sub_f32_e32 v73, v75, v85
	v_mul_f32_e32 v73, 0x3fb8aa3b, v73
	v_exp_f32_e32 v73, v73
	v_pk_mul_f32 v[70:71], v[70:71], v[74:75] op_sel_hi:[1,0]
	v_pk_mul_f32 v[68:69], v[68:69], v[74:75] op_sel_hi:[1,0]
	v_pk_mul_f32 v[66:67], v[66:67], v[74:75] op_sel_hi:[1,0]
	v_cndmask_b32_e32 v73, 0, v73, vcc
	v_pk_mul_f32 v[64:65], v[64:65], v[74:75] op_sel_hi:[1,0]
	v_pk_mul_f32 v[62:63], v[62:63], v[74:75] op_sel_hi:[1,0]
	v_pk_mul_f32 v[60:61], v[60:61], v[74:75] op_sel_hi:[1,0]
	v_pk_mul_f32 v[58:59], v[58:59], v[74:75] op_sel_hi:[1,0]
	v_pk_mul_f32 v[56:57], v[56:57], v[74:75] op_sel_hi:[1,0]
	v_fma_f32 v72, v72, v74, v73
	v_sub_f32_e32 v74, v87, v85
	v_mul_f32_e32 v74, 0x3fb8aa3b, v74
	v_sub_f32_e32 v75, v108, v85
	v_exp_f32_e32 v74, v74
	v_mul_f32_e32 v75, 0x3fb8aa3b, v75
	v_sub_f32_e32 v87, v109, v85
	v_exp_f32_e32 v75, v75
	v_mul_f32_e32 v87, 0x3fb8aa3b, v87
	v_sub_f32_e32 v108, v110, v85
	v_exp_f32_e32 v87, v87
	v_mul_f32_e32 v108, 0x3fb8aa3b, v108
	v_sub_f32_e32 v109, v111, v85
	v_exp_f32_e32 v108, v108
	v_mul_f32_e32 v109, 0x3fb8aa3b, v109
	v_sub_f32_e32 v110, v112, v85
	v_cndmask_b32_e64 v74, 0, v74, s[48:49]
	v_exp_f32_e32 v109, v109
	v_mul_f32_e32 v110, 0x3fb8aa3b, v110
	v_add_f32_e32 v72, v74, v72
	v_cndmask_b32_e64 v75, 0, v75, s[50:51]
	v_exp_f32_e32 v110, v110
	v_add_f32_e32 v72, v75, v72
	v_cndmask_b32_e64 v87, 0, v87, s[52:53]
	v_add_f32_e32 v72, v87, v72
	v_cndmask_b32_e64 v108, 0, v108, s[54:55]
	v_add_f32_e32 v72, v108, v72
	v_cndmask_b32_e64 v109, 0, v109, s[60:61]
	v_add_f32_e32 v72, v109, v72
	v_cndmask_b32_e64 v110, 0, v110, s[62:63]
	v_add_f32_e32 v116, v110, v72
	v_sub_f32_e32 v72, v113, v85
	v_mul_f32_e32 v72, 0x3fb8aa3b, v72
	v_exp_f32_e32 v72, v72
	v_add_u32_e32 v83, 32, v83
	v_add_u32_e32 v107, 32, v107
	v_add_u32_e32 v84, 0x1200, v84
	v_cndmask_b32_e64 v117, 0, v72, s[58:59]
	v_cvt_pk_bf16_f32 v72, v73, v74
	v_cvt_pk_bf16_f32 v73, v75, v87
	v_cvt_pk_bf16_f32 v74, v108, v109
	v_cvt_pk_bf16_f32 v75, v110, v117
	v_add_u32_e32 v86, 0x1100, v86
	s_cmp_gt_u32 s25, 3
	s_waitcnt lgkmcnt(4)
	v_mfma_f32_16x16x32_bf16 v[68:71], v[120:123], v[72:75], v[68:71]
	v_mfma_f32_16x16x32_bf16 v[60:63], v[128:131], v[72:75], v[60:63]
	v_mfma_f32_16x16x32_bf16 v[64:67], v[124:127], v[72:75], v[64:67]
	v_mfma_f32_16x16x32_bf16 v[56:59], v[132:135], v[72:75], v[56:59]
	v_add_f32_e32 v72, v117, v116
	s_cbranch_scc0 .LBB0_313
	s_waitcnt lgkmcnt(0)
	s_branch .LBB0_315
